# P4/P9: hand-written SwiGLU epilogue: rms partials prefetched one tile ahead, batched reduction + v_rsq, scalar f32 math without pack/unpack moves
# baseline (speedup 1.0000x reference)
.LBB0_477:
	s_add_u32 s26, s6, 0x8800000
	s_addc_u32 s27, s7, 0
	s_lshl_b32 s28, s28, 5
	s_and_b32 s36, s28, 0x60
	s_mov_b64 s[28:29], 0x80
	s_add_i32 m0, s42, 0x18000
	v_lshl_add_u64 v[6:7], v[6:7], 0, s[28:29]
	s_lshl_b32 s9, s30, 13
	s_lshl_b32 s31, s36, 7
	s_waitcnt vmcnt(2)
	s_barrier
	global_load_lds_dwordx4 v[6:7], off
	v_lshl_add_u64 v[4:5], v[4:5], 0, s[28:29]
	s_add_i32 m0, s42, 0x1a000
	s_add_i32 s47, s42, 0x8000
	s_add_i32 s48, s42, 0xa000
	global_load_lds_dwordx4 v[4:5], off
	v_lshl_add_u64 v[0:1], v[0:1], 0, s[28:29]
	s_mov_b32 m0, s47
	s_add_u32 s34, s4, 0x40080
	global_load_lds_dwordx4 v[0:1], off
	v_lshl_add_u64 v[0:1], v[2:3], 0, s[28:29]
	s_mov_b32 m0, s48
	s_addc_u32 s35, s5, 0
	global_load_lds_dwordx4 v[0:1], off
	s_add_i32 m0, s42, 0x1c000
	v_lshl_add_u64 v[0:1], s[34:35], 0, v[132:133]
	global_load_lds_dwordx4 v[0:1], off
	v_lshl_add_u64 v[0:1], s[34:35], 0, v[128:129]
	s_add_i32 m0, s42, 0x1e000
	v_bfe_u32 v2, v9, 4, 2
	global_load_lds_dwordx4 v[0:1], off
	v_and_b32_e32 v1, 15, v9
	v_lshlrev_b32_e32 v0, 4, v2
	v_lshlrev_b32_e32 v3, 2, v9
	v_lshl_or_b32 v159, s30, 6, v1
	v_lshl_or_b32 v1, v1, 6, v0
	v_and_b32_e32 v3, 32, v3
	v_bitop3_b32 v4, v1, s9, v3 bitop3:0xde
	v_bitop3_b32 v165, v1, s31, v3 bitop3:0xde
	v_mov_b32_e32 v1, v133
	v_lshl_add_u64 v[0:1], s[6:7], 0, v[0:1]
	s_mov_b64 s[6:7], 0x200000
	v_lshl_add_u64 v[136:137], v[0:1], 0, s[6:7]
	v_lshlrev_b32_e32 v0, 14, v13
	v_and_b32_e32 v0, 0xffff8000, v0
	v_lshl_add_u32 v0, v12, 11, v0
	v_and_b32_e32 v1, 1, v13
	v_lshl_or_b32 v0, v1, 6, v0
	v_lshl_add_u32 v138, v14, 1, v0
	v_lshlrev_b32_e32 v0, 14, v8
	v_and_b32_e32 v0, 0xffff8000, v0
	s_waitcnt vmcnt(6)
	s_cmpk_lt_u32 s13, 0x100
	v_lshl_add_u32 v0, v10, 11, v0
	v_and_b32_e32 v1, 1, v8
	s_cselect_b64 s[30:31], -1, 0
	v_lshl_or_b32 v0, v1, 6, v0
	s_add_i32 s49, 0, 0x10000
	s_add_i32 s50, 0, 0x14000
	s_sext_i32_i16 s33, s12
	v_lshl_or_b32 v167, v2, 3, s36
	v_mov_b32_e32 v139, v133
	v_lshl_add_u32 v140, v11, 1, v0
	v_mov_b32_e32 v141, v133
	v_mov_b64_e32 v[142:143], 0xb00
	v_mov_b64_e32 v[144:145], 0xaff
	v_add_u32_e32 v169, s49, v165
	v_add_u32_e32 v171, s50, v165
	v_add_u32_e32 v173, 0, v4
	v_mbcnt_hi_u32_b32 v175, -1, v203
	v_mov_b32_e32 v177, 0x3727c5ac
	s_mov_b32 s51, 0xf800000
	v_mov_b32_e32 v178, 0x260
	s_movk_i32 s52, 0x1600
	s_barrier
	v_lshl_add_u32 v249, s8, 8, v159
	s_mov_b64 s[60:61], 0x2000
	v_lshlrev_b32_e32 v204, 6, v249
	v_mov_b32_e32 v205, 0
	v_lshl_add_u64 v[204:205], v[136:137], 0, v[204:205]
	v_lshl_add_u64 v[206:207], v[204:205], 0, s[60:61]
	global_load_dwordx4 v[208:211], v[204:205], off
	global_load_dwordx4 v[212:215], v[204:205], off offset:1024
	global_load_dwordx4 v[216:219], v[204:205], off offset:2048
	global_load_dwordx4 v[220:223], v[204:205], off offset:3072
	global_load_dwordx4 v[224:227], v[206:207], off
	global_load_dwordx4 v[228:231], v[206:207], off offset:1024
	global_load_dwordx4 v[232:235], v[206:207], off offset:2048
	global_load_dwordx4 v[236:239], v[206:207], off offset:3072
	s_waitcnt vmcnt(0)
	v_mbcnt_lo_u32_b32 v248, -1, 0
	v_mbcnt_hi_u32_b32 v248, -1, v248
	v_add_f32_e32 v208, v208, v209
	v_add_f32_e32 v210, v210, v211
	v_add_f32_e32 v212, v212, v213
	v_add_f32_e32 v214, v214, v215
	v_add_f32_e32 v216, v216, v217
	v_add_f32_e32 v218, v218, v219
	v_add_f32_e32 v220, v220, v221
	v_add_f32_e32 v222, v222, v223
	v_add_f32_e32 v224, v224, v225
	v_add_f32_e32 v226, v226, v227
	v_add_f32_e32 v228, v228, v229
	v_add_f32_e32 v230, v230, v231
	v_add_f32_e32 v232, v232, v233
	v_add_f32_e32 v234, v234, v235
	v_add_f32_e32 v236, v236, v237
	v_add_f32_e32 v238, v238, v239
	v_xor_b32_e32 v248, 16, v248
	v_lshlrev_b32_e32 v248, 2, v248
	v_add_f32_e32 v208, v208, v210
	v_add_f32_e32 v212, v212, v214
	v_add_f32_e32 v216, v216, v218
	v_add_f32_e32 v220, v220, v222
	v_add_f32_e32 v224, v224, v226
	v_add_f32_e32 v228, v228, v230
	v_add_f32_e32 v232, v232, v234
	v_add_f32_e32 v236, v236, v238
	ds_bpermute_b32 v209, v248, v208
	ds_bpermute_b32 v213, v248, v212
	ds_bpermute_b32 v217, v248, v216
	ds_bpermute_b32 v221, v248, v220
	ds_bpermute_b32 v225, v248, v224
	ds_bpermute_b32 v229, v248, v228
	ds_bpermute_b32 v233, v248, v232
	ds_bpermute_b32 v237, v248, v236
	s_waitcnt lgkmcnt(0)
	v_add_f32_e32 v208, v208, v209
	v_add_f32_e32 v212, v212, v213
	v_add_f32_e32 v216, v216, v217
	v_add_f32_e32 v220, v220, v221
	v_add_f32_e32 v224, v224, v225
	v_add_f32_e32 v228, v228, v229
	v_add_f32_e32 v232, v232, v233
	v_add_f32_e32 v236, v236, v237
	v_mov_b32_e32 v209, v208
	v_mov_b32_e32 v213, v212
	v_mov_b32_e32 v217, v216
	v_mov_b32_e32 v221, v220
	v_mov_b32_e32 v225, v224
	v_mov_b32_e32 v229, v228
	v_mov_b32_e32 v233, v232
	v_mov_b32_e32 v237, v236
	s_nop 1
	v_permlane32_swap_b32_e32 v208, v209
	v_permlane32_swap_b32_e32 v212, v213
	v_permlane32_swap_b32_e32 v216, v217
	v_permlane32_swap_b32_e32 v220, v221
	v_permlane32_swap_b32_e32 v224, v225
	v_permlane32_swap_b32_e32 v228, v229
	v_permlane32_swap_b32_e32 v232, v233
	v_permlane32_swap_b32_e32 v236, v237
	v_add_f32_e32 v208, v208, v209
	v_add_f32_e32 v212, v212, v213
	v_add_f32_e32 v216, v216, v217
	v_add_f32_e32 v220, v220, v221
	v_add_f32_e32 v224, v224, v225
	v_add_f32_e32 v228, v228, v229
	v_add_f32_e32 v232, v232, v233
	v_add_f32_e32 v236, v236, v237
	v_fmamk_f32 v208, v208, 0x3a800000, v177
	v_fmamk_f32 v212, v212, 0x3a800000, v177
	v_fmamk_f32 v216, v216, 0x3a800000, v177
	v_fmamk_f32 v220, v220, 0x3a800000, v177
	v_fmamk_f32 v224, v224, 0x3a800000, v177
	v_fmamk_f32 v228, v228, 0x3a800000, v177
	v_fmamk_f32 v232, v232, 0x3a800000, v177
	v_fmamk_f32 v236, v236, 0x3a800000, v177
	v_rsq_f32_e32 v240, v208
	v_rsq_f32_e32 v241, v212
	v_rsq_f32_e32 v242, v216
	v_rsq_f32_e32 v243, v220
	v_rsq_f32_e32 v244, v224
	v_rsq_f32_e32 v245, v228
	v_rsq_f32_e32 v246, v232
	v_rsq_f32_e32 v247, v236
	s_nop 0
	s_branch .LBB0_480

.LBB0_486:
	s_cmp_lg_u64 s[6:7], 0
	s_cselect_b32 s62, s36, s8
	v_lshl_add_u32 v249, s62, 8, v159
	s_mov_b64 s[60:61], 0x2000
	v_lshlrev_b32_e32 v204, 6, v249
	v_mov_b32_e32 v205, 0
	v_lshl_add_u64 v[204:205], v[136:137], 0, v[204:205]
	v_lshl_add_u64 v[206:207], v[204:205], 0, s[60:61]
	global_load_dwordx4 v[208:211], v[204:205], off
	global_load_dwordx4 v[212:215], v[204:205], off offset:1024
	global_load_dwordx4 v[216:219], v[204:205], off offset:2048
	global_load_dwordx4 v[220:223], v[204:205], off offset:3072
	global_load_dwordx4 v[224:227], v[206:207], off
	global_load_dwordx4 v[228:231], v[206:207], off offset:1024
	global_load_dwordx4 v[232:235], v[206:207], off offset:2048
	global_load_dwordx4 v[236:239], v[206:207], off offset:3072
	v_lshl_or_b32 v252, s33, 7, v167
	v_lshlrev_b32_e32 v252, 1, v252
	v_mov_b32_e32 v253, 0
	v_lshl_add_u64 v[252:253], s[26:27], 0, v[252:253]
	v_lshl_add_u32 v206, s8, 8, v159
	v_mov_b32_e32 v154, v206
	v_mul_f32_e32 v207, 0xbfb8aa3b, v240
	v_mad_u64_u32 v[204:205], vcc, v154, s52, v[252:253]
	v_mul_f32_e32 v146, v124, v207
	v_mul_f32_e32 v147, v125, v207
	v_mul_f32_e32 v148, v126, v207
	v_mul_f32_e32 v149, v127, v207
	v_mul_f32_e32 v150, v116, v207
	v_mul_f32_e32 v151, v117, v207
	v_mul_f32_e32 v152, v118, v207
	v_mul_f32_e32 v153, v119, v207
	v_exp_f32_e32 v146, v146
	v_exp_f32_e32 v147, v147
	v_exp_f32_e32 v148, v148
	v_exp_f32_e32 v149, v149
	v_exp_f32_e32 v150, v150
	v_exp_f32_e32 v151, v151
	v_exp_f32_e32 v152, v152
	v_exp_f32_e32 v153, v153
	v_mul_f32_e32 v124, v124, v240
	v_mul_f32_e32 v125, v125, v240
	v_mul_f32_e32 v126, v126, v240
	v_mul_f32_e32 v127, v127, v240
	v_mul_f32_e32 v116, v116, v240
	v_mul_f32_e32 v117, v117, v240
	v_mul_f32_e32 v118, v118, v240
	v_mul_f32_e32 v119, v119, v240
	v_add_f32_e32 v146, 1.0, v146
	v_add_f32_e32 v147, 1.0, v147
	v_add_f32_e32 v148, 1.0, v148
	v_add_f32_e32 v149, 1.0, v149
	v_add_f32_e32 v150, 1.0, v150
	v_add_f32_e32 v151, 1.0, v151
	v_add_f32_e32 v152, 1.0, v152
	v_add_f32_e32 v153, 1.0, v153
	v_rcp_f32_e32 v146, v146
	v_rcp_f32_e32 v147, v147
	v_rcp_f32_e32 v148, v148
	v_rcp_f32_e32 v149, v149
	v_rcp_f32_e32 v150, v150
	v_rcp_f32_e32 v151, v151
	v_rcp_f32_e32 v152, v152
	v_rcp_f32_e32 v153, v153
	v_mul_f32_e32 v120, v120, v240
	v_mul_f32_e32 v121, v121, v240
	v_mul_f32_e32 v122, v122, v240
	v_mul_f32_e32 v123, v123, v240
	v_mul_f32_e32 v112, v112, v240
	v_mul_f32_e32 v113, v113, v240
	v_mul_f32_e32 v114, v114, v240
	v_mul_f32_e32 v115, v115, v240
	v_mul_f32_e32 v124, v124, v146
	v_mul_f32_e32 v125, v125, v147
	v_mul_f32_e32 v126, v126, v148
	v_mul_f32_e32 v127, v127, v149
	v_mul_f32_e32 v116, v116, v150
	v_mul_f32_e32 v117, v117, v151
	v_mul_f32_e32 v118, v118, v152
	v_mul_f32_e32 v119, v119, v153
	v_mul_f32_e32 v124, v124, v120
	v_mul_f32_e32 v125, v125, v121
	v_mul_f32_e32 v126, v126, v122
	v_mul_f32_e32 v127, v127, v123
	v_mul_f32_e32 v116, v116, v112
	v_mul_f32_e32 v117, v117, v113
	v_mul_f32_e32 v118, v118, v114
	v_mul_f32_e32 v119, v119, v115
	v_cvt_pk_bf16_f32 v120, v124, v125
	v_cvt_pk_bf16_f32 v121, v126, v127
	v_cvt_pk_bf16_f32 v122, v116, v117
	v_cvt_pk_bf16_f32 v123, v118, v119
	global_store_dwordx4 v[204:205], v[120:123], off
	v_add_u32_e32 v154, 16, v206
	v_mul_f32_e32 v207, 0xbfb8aa3b, v241
	v_mad_u64_u32 v[204:205], vcc, v154, s52, v[252:253]
	v_mul_f32_e32 v146, v108, v207
	v_mul_f32_e32 v147, v109, v207
	v_mul_f32_e32 v148, v110, v207
	v_mul_f32_e32 v149, v111, v207
	v_mul_f32_e32 v150, v100, v207
	v_mul_f32_e32 v151, v101, v207
	v_mul_f32_e32 v152, v102, v207
	v_mul_f32_e32 v153, v103, v207
	v_exp_f32_e32 v146, v146
	v_exp_f32_e32 v147, v147
	v_exp_f32_e32 v148, v148
	v_exp_f32_e32 v149, v149
	v_exp_f32_e32 v150, v150
	v_exp_f32_e32 v151, v151
	v_exp_f32_e32 v152, v152
	v_exp_f32_e32 v153, v153
	v_mul_f32_e32 v108, v108, v241
	v_mul_f32_e32 v109, v109, v241
	v_mul_f32_e32 v110, v110, v241
	v_mul_f32_e32 v111, v111, v241
	v_mul_f32_e32 v100, v100, v241
	v_mul_f32_e32 v101, v101, v241
	v_mul_f32_e32 v102, v102, v241
	v_mul_f32_e32 v103, v103, v241
	v_add_f32_e32 v146, 1.0, v146
	v_add_f32_e32 v147, 1.0, v147
	v_add_f32_e32 v148, 1.0, v148
	v_add_f32_e32 v149, 1.0, v149
	v_add_f32_e32 v150, 1.0, v150
	v_add_f32_e32 v151, 1.0, v151
	v_add_f32_e32 v152, 1.0, v152
	v_add_f32_e32 v153, 1.0, v153
	v_rcp_f32_e32 v146, v146
	v_rcp_f32_e32 v147, v147
	v_rcp_f32_e32 v148, v148
	v_rcp_f32_e32 v149, v149
	v_rcp_f32_e32 v150, v150
	v_rcp_f32_e32 v151, v151
	v_rcp_f32_e32 v152, v152
	v_rcp_f32_e32 v153, v153
	v_mul_f32_e32 v104, v104, v241
	v_mul_f32_e32 v105, v105, v241
	v_mul_f32_e32 v106, v106, v241
	v_mul_f32_e32 v107, v107, v241
	v_mul_f32_e32 v96, v96, v241
	v_mul_f32_e32 v97, v97, v241
	v_mul_f32_e32 v98, v98, v241
	v_mul_f32_e32 v99, v99, v241
	v_mul_f32_e32 v108, v108, v146
	v_mul_f32_e32 v109, v109, v147
	v_mul_f32_e32 v110, v110, v148
	v_mul_f32_e32 v111, v111, v149
	v_mul_f32_e32 v100, v100, v150
	v_mul_f32_e32 v101, v101, v151
	v_mul_f32_e32 v102, v102, v152
	v_mul_f32_e32 v103, v103, v153
	v_mul_f32_e32 v108, v108, v104
	v_mul_f32_e32 v109, v109, v105
	v_mul_f32_e32 v110, v110, v106
	v_mul_f32_e32 v111, v111, v107
	v_mul_f32_e32 v100, v100, v96
	v_mul_f32_e32 v101, v101, v97
	v_mul_f32_e32 v102, v102, v98
	v_mul_f32_e32 v103, v103, v99
	v_cvt_pk_bf16_f32 v104, v108, v109
	v_cvt_pk_bf16_f32 v105, v110, v111
	v_cvt_pk_bf16_f32 v106, v100, v101
	v_cvt_pk_bf16_f32 v107, v102, v103
	global_store_dwordx4 v[204:205], v[104:107], off
	v_add_u32_e32 v154, 32, v206
	v_mul_f32_e32 v207, 0xbfb8aa3b, v242
	v_mad_u64_u32 v[204:205], vcc, v154, s52, v[252:253]
	v_mul_f32_e32 v146, v92, v207
	v_mul_f32_e32 v147, v93, v207
	v_mul_f32_e32 v148, v94, v207
	v_mul_f32_e32 v149, v95, v207
	v_mul_f32_e32 v150, v84, v207
	v_mul_f32_e32 v151, v85, v207
	v_mul_f32_e32 v152, v86, v207
	v_mul_f32_e32 v153, v87, v207
	v_exp_f32_e32 v146, v146
	v_exp_f32_e32 v147, v147
	v_exp_f32_e32 v148, v148
	v_exp_f32_e32 v149, v149
	v_exp_f32_e32 v150, v150
	v_exp_f32_e32 v151, v151
	v_exp_f32_e32 v152, v152
	v_exp_f32_e32 v153, v153
	v_mul_f32_e32 v92, v92, v242
	v_mul_f32_e32 v93, v93, v242
	v_mul_f32_e32 v94, v94, v242
	v_mul_f32_e32 v95, v95, v242
	v_mul_f32_e32 v84, v84, v242
	v_mul_f32_e32 v85, v85, v242
	v_mul_f32_e32 v86, v86, v242
	v_mul_f32_e32 v87, v87, v242
	v_add_f32_e32 v146, 1.0, v146
	v_add_f32_e32 v147, 1.0, v147
	v_add_f32_e32 v148, 1.0, v148
	v_add_f32_e32 v149, 1.0, v149
	v_add_f32_e32 v150, 1.0, v150
	v_add_f32_e32 v151, 1.0, v151
	v_add_f32_e32 v152, 1.0, v152
	v_add_f32_e32 v153, 1.0, v153
	v_rcp_f32_e32 v146, v146
	v_rcp_f32_e32 v147, v147
	v_rcp_f32_e32 v148, v148
	v_rcp_f32_e32 v149, v149
	v_rcp_f32_e32 v150, v150
	v_rcp_f32_e32 v151, v151
	v_rcp_f32_e32 v152, v152
	v_rcp_f32_e32 v153, v153
	v_mul_f32_e32 v88, v88, v242
	v_mul_f32_e32 v89, v89, v242
	v_mul_f32_e32 v90, v90, v242
	v_mul_f32_e32 v91, v91, v242
	v_mul_f32_e32 v80, v80, v242
	v_mul_f32_e32 v81, v81, v242
	v_mul_f32_e32 v82, v82, v242
	v_mul_f32_e32 v83, v83, v242
	v_mul_f32_e32 v92, v92, v146
	v_mul_f32_e32 v93, v93, v147
	v_mul_f32_e32 v94, v94, v148
	v_mul_f32_e32 v95, v95, v149
	v_mul_f32_e32 v84, v84, v150
	v_mul_f32_e32 v85, v85, v151
	v_mul_f32_e32 v86, v86, v152
	v_mul_f32_e32 v87, v87, v153
	v_mul_f32_e32 v92, v92, v88
	v_mul_f32_e32 v93, v93, v89
	v_mul_f32_e32 v94, v94, v90
	v_mul_f32_e32 v95, v95, v91
	v_mul_f32_e32 v84, v84, v80
	v_mul_f32_e32 v85, v85, v81
	v_mul_f32_e32 v86, v86, v82
	v_mul_f32_e32 v87, v87, v83
	v_cvt_pk_bf16_f32 v88, v92, v93
	v_cvt_pk_bf16_f32 v89, v94, v95
	v_cvt_pk_bf16_f32 v90, v84, v85
	v_cvt_pk_bf16_f32 v91, v86, v87
	global_store_dwordx4 v[204:205], v[88:91], off
	v_add_u32_e32 v154, 48, v206
	v_mul_f32_e32 v207, 0xbfb8aa3b, v243
	v_mad_u64_u32 v[204:205], vcc, v154, s52, v[252:253]
	v_mul_f32_e32 v146, v76, v207
	v_mul_f32_e32 v147, v77, v207
	v_mul_f32_e32 v148, v78, v207
	v_mul_f32_e32 v149, v79, v207
	v_mul_f32_e32 v150, v68, v207
	v_mul_f32_e32 v151, v69, v207
	v_mul_f32_e32 v152, v70, v207
	v_mul_f32_e32 v153, v71, v207
	v_exp_f32_e32 v146, v146
	v_exp_f32_e32 v147, v147
	v_exp_f32_e32 v148, v148
	v_exp_f32_e32 v149, v149
	v_exp_f32_e32 v150, v150
	v_exp_f32_e32 v151, v151
	v_exp_f32_e32 v152, v152
	v_exp_f32_e32 v153, v153
	v_mul_f32_e32 v76, v76, v243
	v_mul_f32_e32 v77, v77, v243
	v_mul_f32_e32 v78, v78, v243
	v_mul_f32_e32 v79, v79, v243
	v_mul_f32_e32 v68, v68, v243
	v_mul_f32_e32 v69, v69, v243
	v_mul_f32_e32 v70, v70, v243
	v_mul_f32_e32 v71, v71, v243
	v_add_f32_e32 v146, 1.0, v146
	v_add_f32_e32 v147, 1.0, v147
	v_add_f32_e32 v148, 1.0, v148
	v_add_f32_e32 v149, 1.0, v149
	v_add_f32_e32 v150, 1.0, v150
	v_add_f32_e32 v151, 1.0, v151
	v_add_f32_e32 v152, 1.0, v152
	v_add_f32_e32 v153, 1.0, v153
	v_rcp_f32_e32 v146, v146
	v_rcp_f32_e32 v147, v147
	v_rcp_f32_e32 v148, v148
	v_rcp_f32_e32 v149, v149
	v_rcp_f32_e32 v150, v150
	v_rcp_f32_e32 v151, v151
	v_rcp_f32_e32 v152, v152
	v_rcp_f32_e32 v153, v153
	v_mul_f32_e32 v72, v72, v243
	v_mul_f32_e32 v73, v73, v243
	v_mul_f32_e32 v74, v74, v243
	v_mul_f32_e32 v75, v75, v243
	v_mul_f32_e32 v64, v64, v243
	v_mul_f32_e32 v65, v65, v243
	v_mul_f32_e32 v66, v66, v243
	v_mul_f32_e32 v67, v67, v243
	v_mul_f32_e32 v76, v76, v146
	v_mul_f32_e32 v77, v77, v147
	v_mul_f32_e32 v78, v78, v148
	v_mul_f32_e32 v79, v79, v149
	v_mul_f32_e32 v68, v68, v150
	v_mul_f32_e32 v69, v69, v151
	v_mul_f32_e32 v70, v70, v152
	v_mul_f32_e32 v71, v71, v153
	v_mul_f32_e32 v76, v76, v72
	v_mul_f32_e32 v77, v77, v73
	v_mul_f32_e32 v78, v78, v74
	v_mul_f32_e32 v79, v79, v75
	v_mul_f32_e32 v68, v68, v64
	v_mul_f32_e32 v69, v69, v65
	v_mul_f32_e32 v70, v70, v66
	v_mul_f32_e32 v71, v71, v67
	v_cvt_pk_bf16_f32 v72, v76, v77
	v_cvt_pk_bf16_f32 v73, v78, v79
	v_cvt_pk_bf16_f32 v74, v68, v69
	v_cvt_pk_bf16_f32 v75, v70, v71
	global_store_dwordx4 v[204:205], v[72:75], off
	v_add_u32_e32 v154, 128, v206
	v_mul_f32_e32 v207, 0xbfb8aa3b, v244
	v_mad_u64_u32 v[204:205], vcc, v154, s52, v[252:253]
	v_mul_f32_e32 v146, v60, v207
	v_mul_f32_e32 v147, v61, v207
	v_mul_f32_e32 v148, v62, v207
	v_mul_f32_e32 v149, v63, v207
	v_mul_f32_e32 v150, v52, v207
	v_mul_f32_e32 v151, v53, v207
	v_mul_f32_e32 v152, v54, v207
	v_mul_f32_e32 v153, v55, v207
	v_exp_f32_e32 v146, v146
	v_exp_f32_e32 v147, v147
	v_exp_f32_e32 v148, v148
	v_exp_f32_e32 v149, v149
	v_exp_f32_e32 v150, v150
	v_exp_f32_e32 v151, v151
	v_exp_f32_e32 v152, v152
	v_exp_f32_e32 v153, v153
	v_mul_f32_e32 v60, v60, v244
	v_mul_f32_e32 v61, v61, v244
	v_mul_f32_e32 v62, v62, v244
	v_mul_f32_e32 v63, v63, v244
	v_mul_f32_e32 v52, v52, v244
	v_mul_f32_e32 v53, v53, v244
	v_mul_f32_e32 v54, v54, v244
	v_mul_f32_e32 v55, v55, v244
	v_add_f32_e32 v146, 1.0, v146
	v_add_f32_e32 v147, 1.0, v147
	v_add_f32_e32 v148, 1.0, v148
	v_add_f32_e32 v149, 1.0, v149
	v_add_f32_e32 v150, 1.0, v150
	v_add_f32_e32 v151, 1.0, v151
	v_add_f32_e32 v152, 1.0, v152
	v_add_f32_e32 v153, 1.0, v153
	v_rcp_f32_e32 v146, v146
	v_rcp_f32_e32 v147, v147
	v_rcp_f32_e32 v148, v148
	v_rcp_f32_e32 v149, v149
	v_rcp_f32_e32 v150, v150
	v_rcp_f32_e32 v151, v151
	v_rcp_f32_e32 v152, v152
	v_rcp_f32_e32 v153, v153
	v_mul_f32_e32 v56, v56, v244
	v_mul_f32_e32 v57, v57, v244
	v_mul_f32_e32 v58, v58, v244
	v_mul_f32_e32 v59, v59, v244
	v_mul_f32_e32 v48, v48, v244
	v_mul_f32_e32 v49, v49, v244
	v_mul_f32_e32 v50, v50, v244
	v_mul_f32_e32 v51, v51, v244
	v_mul_f32_e32 v60, v60, v146
	v_mul_f32_e32 v61, v61, v147
	v_mul_f32_e32 v62, v62, v148
	v_mul_f32_e32 v63, v63, v149
	v_mul_f32_e32 v52, v52, v150
	v_mul_f32_e32 v53, v53, v151
	v_mul_f32_e32 v54, v54, v152
	v_mul_f32_e32 v55, v55, v153
	v_mul_f32_e32 v60, v60, v56
	v_mul_f32_e32 v61, v61, v57
	v_mul_f32_e32 v62, v62, v58
	v_mul_f32_e32 v63, v63, v59
	v_mul_f32_e32 v52, v52, v48
	v_mul_f32_e32 v53, v53, v49
	v_mul_f32_e32 v54, v54, v50
	v_mul_f32_e32 v55, v55, v51
	v_cvt_pk_bf16_f32 v56, v60, v61
	v_cvt_pk_bf16_f32 v57, v62, v63
	v_cvt_pk_bf16_f32 v58, v52, v53
	v_cvt_pk_bf16_f32 v59, v54, v55
	global_store_dwordx4 v[204:205], v[56:59], off
	v_add_u32_e32 v154, 144, v206
	v_mul_f32_e32 v207, 0xbfb8aa3b, v245
	v_mad_u64_u32 v[204:205], vcc, v154, s52, v[252:253]
	v_mul_f32_e32 v146, v44, v207
	v_mul_f32_e32 v147, v45, v207
	v_mul_f32_e32 v148, v46, v207
	v_mul_f32_e32 v149, v47, v207
	v_mul_f32_e32 v150, v36, v207
	v_mul_f32_e32 v151, v37, v207
	v_mul_f32_e32 v152, v38, v207
	v_mul_f32_e32 v153, v39, v207
	v_exp_f32_e32 v146, v146
	v_exp_f32_e32 v147, v147
	v_exp_f32_e32 v148, v148
	v_exp_f32_e32 v149, v149
	v_exp_f32_e32 v150, v150
	v_exp_f32_e32 v151, v151
	v_exp_f32_e32 v152, v152
	v_exp_f32_e32 v153, v153
	v_mul_f32_e32 v44, v44, v245
	v_mul_f32_e32 v45, v45, v245
	v_mul_f32_e32 v46, v46, v245
	v_mul_f32_e32 v47, v47, v245
	v_mul_f32_e32 v36, v36, v245
	v_mul_f32_e32 v37, v37, v245
	v_mul_f32_e32 v38, v38, v245
	v_mul_f32_e32 v39, v39, v245
	v_add_f32_e32 v146, 1.0, v146
	v_add_f32_e32 v147, 1.0, v147
	v_add_f32_e32 v148, 1.0, v148
	v_add_f32_e32 v149, 1.0, v149
	v_add_f32_e32 v150, 1.0, v150
	v_add_f32_e32 v151, 1.0, v151
	v_add_f32_e32 v152, 1.0, v152
	v_add_f32_e32 v153, 1.0, v153
	v_rcp_f32_e32 v146, v146
	v_rcp_f32_e32 v147, v147
	v_rcp_f32_e32 v148, v148
	v_rcp_f32_e32 v149, v149
	v_rcp_f32_e32 v150, v150
	v_rcp_f32_e32 v151, v151
	v_rcp_f32_e32 v152, v152
	v_rcp_f32_e32 v153, v153
	v_mul_f32_e32 v40, v40, v245
	v_mul_f32_e32 v41, v41, v245
	v_mul_f32_e32 v42, v42, v245
	v_mul_f32_e32 v43, v43, v245
	v_mul_f32_e32 v32, v32, v245
	v_mul_f32_e32 v33, v33, v245
	v_mul_f32_e32 v34, v34, v245
	v_mul_f32_e32 v35, v35, v245
	v_mul_f32_e32 v44, v44, v146
	v_mul_f32_e32 v45, v45, v147
	v_mul_f32_e32 v46, v46, v148
	v_mul_f32_e32 v47, v47, v149
	v_mul_f32_e32 v36, v36, v150
	v_mul_f32_e32 v37, v37, v151
	v_mul_f32_e32 v38, v38, v152
	v_mul_f32_e32 v39, v39, v153
	v_mul_f32_e32 v44, v44, v40
	v_mul_f32_e32 v45, v45, v41
	v_mul_f32_e32 v46, v46, v42
	v_mul_f32_e32 v47, v47, v43
	v_mul_f32_e32 v36, v36, v32
	v_mul_f32_e32 v37, v37, v33
	v_mul_f32_e32 v38, v38, v34
	v_mul_f32_e32 v39, v39, v35
	v_cvt_pk_bf16_f32 v40, v44, v45
	v_cvt_pk_bf16_f32 v41, v46, v47
	v_cvt_pk_bf16_f32 v42, v36, v37
	v_cvt_pk_bf16_f32 v43, v38, v39
	global_store_dwordx4 v[204:205], v[40:43], off
	v_add_u32_e32 v154, 160, v206
	v_mul_f32_e32 v207, 0xbfb8aa3b, v246
	v_mad_u64_u32 v[204:205], vcc, v154, s52, v[252:253]
	v_mul_f32_e32 v146, v28, v207
	v_mul_f32_e32 v147, v29, v207
	v_mul_f32_e32 v148, v30, v207
	v_mul_f32_e32 v149, v31, v207
	v_mul_f32_e32 v150, v20, v207
	v_mul_f32_e32 v151, v21, v207
	v_mul_f32_e32 v152, v22, v207
	v_mul_f32_e32 v153, v23, v207
	v_exp_f32_e32 v146, v146
	v_exp_f32_e32 v147, v147
	v_exp_f32_e32 v148, v148
	v_exp_f32_e32 v149, v149
	v_exp_f32_e32 v150, v150
	v_exp_f32_e32 v151, v151
	v_exp_f32_e32 v152, v152
	v_exp_f32_e32 v153, v153
	v_mul_f32_e32 v28, v28, v246
	v_mul_f32_e32 v29, v29, v246
	v_mul_f32_e32 v30, v30, v246
	v_mul_f32_e32 v31, v31, v246
	v_mul_f32_e32 v20, v20, v246
	v_mul_f32_e32 v21, v21, v246
	v_mul_f32_e32 v22, v22, v246
	v_mul_f32_e32 v23, v23, v246
	v_add_f32_e32 v146, 1.0, v146
	v_add_f32_e32 v147, 1.0, v147
	v_add_f32_e32 v148, 1.0, v148
	v_add_f32_e32 v149, 1.0, v149
	v_add_f32_e32 v150, 1.0, v150
	v_add_f32_e32 v151, 1.0, v151
	v_add_f32_e32 v152, 1.0, v152
	v_add_f32_e32 v153, 1.0, v153
	v_rcp_f32_e32 v146, v146
	v_rcp_f32_e32 v147, v147
	v_rcp_f32_e32 v148, v148
	v_rcp_f32_e32 v149, v149
	v_rcp_f32_e32 v150, v150
	v_rcp_f32_e32 v151, v151
	v_rcp_f32_e32 v152, v152
	v_rcp_f32_e32 v153, v153
	v_mul_f32_e32 v24, v24, v246
	v_mul_f32_e32 v25, v25, v246
	v_mul_f32_e32 v26, v26, v246
	v_mul_f32_e32 v27, v27, v246
	v_mul_f32_e32 v16, v16, v246
	v_mul_f32_e32 v17, v17, v246
	v_mul_f32_e32 v18, v18, v246
	v_mul_f32_e32 v19, v19, v246
	v_mul_f32_e32 v28, v28, v146
	v_mul_f32_e32 v29, v29, v147
	v_mul_f32_e32 v30, v30, v148
	v_mul_f32_e32 v31, v31, v149
	v_mul_f32_e32 v20, v20, v150
	v_mul_f32_e32 v21, v21, v151
	v_mul_f32_e32 v22, v22, v152
	v_mul_f32_e32 v23, v23, v153
	v_mul_f32_e32 v28, v28, v24
	v_mul_f32_e32 v29, v29, v25
	v_mul_f32_e32 v30, v30, v26
	v_mul_f32_e32 v31, v31, v27
	v_mul_f32_e32 v20, v20, v16
	v_mul_f32_e32 v21, v21, v17
	v_mul_f32_e32 v22, v22, v18
	v_mul_f32_e32 v23, v23, v19
	v_cvt_pk_bf16_f32 v24, v28, v29
	v_cvt_pk_bf16_f32 v25, v30, v31
	v_cvt_pk_bf16_f32 v26, v20, v21
	v_cvt_pk_bf16_f32 v27, v22, v23
	global_store_dwordx4 v[204:205], v[24:27], off
	v_add_u32_e32 v154, 176, v206
	v_mul_f32_e32 v207, 0xbfb8aa3b, v247
	v_mad_u64_u32 v[204:205], vcc, v154, s52, v[252:253]
	v_mul_f32_e32 v146, v12, v207
	v_mul_f32_e32 v147, v13, v207
	v_mul_f32_e32 v148, v14, v207
	v_mul_f32_e32 v149, v15, v207
	v_mul_f32_e32 v150, v4, v207
	v_mul_f32_e32 v151, v5, v207
	v_mul_f32_e32 v152, v6, v207
	v_mul_f32_e32 v153, v7, v207
	v_exp_f32_e32 v146, v146
	v_exp_f32_e32 v147, v147
	v_exp_f32_e32 v148, v148
	v_exp_f32_e32 v149, v149
	v_exp_f32_e32 v150, v150
	v_exp_f32_e32 v151, v151
	v_exp_f32_e32 v152, v152
	v_exp_f32_e32 v153, v153
	v_mul_f32_e32 v12, v12, v247
	v_mul_f32_e32 v13, v13, v247
	v_mul_f32_e32 v14, v14, v247
	v_mul_f32_e32 v15, v15, v247
	v_mul_f32_e32 v4, v4, v247
	v_mul_f32_e32 v5, v5, v247
	v_mul_f32_e32 v6, v6, v247
	v_mul_f32_e32 v7, v7, v247
	v_add_f32_e32 v146, 1.0, v146
	v_add_f32_e32 v147, 1.0, v147
	v_add_f32_e32 v148, 1.0, v148
	v_add_f32_e32 v149, 1.0, v149
	v_add_f32_e32 v150, 1.0, v150
	v_add_f32_e32 v151, 1.0, v151
	v_add_f32_e32 v152, 1.0, v152
	v_add_f32_e32 v153, 1.0, v153
	v_rcp_f32_e32 v146, v146
	v_rcp_f32_e32 v147, v147
	v_rcp_f32_e32 v148, v148
	v_rcp_f32_e32 v149, v149
	v_rcp_f32_e32 v150, v150
	v_rcp_f32_e32 v151, v151
	v_rcp_f32_e32 v152, v152
	v_rcp_f32_e32 v153, v153
	v_mul_f32_e32 v8, v8, v247
	v_mul_f32_e32 v9, v9, v247
	v_mul_f32_e32 v10, v10, v247
	v_mul_f32_e32 v11, v11, v247
	v_mul_f32_e32 v0, v0, v247
	v_mul_f32_e32 v1, v1, v247
	v_mul_f32_e32 v2, v2, v247
	v_mul_f32_e32 v3, v3, v247
	v_mul_f32_e32 v12, v12, v146
	v_mul_f32_e32 v13, v13, v147
	v_mul_f32_e32 v14, v14, v148
	v_mul_f32_e32 v15, v15, v149
	v_mul_f32_e32 v4, v4, v150
	v_mul_f32_e32 v5, v5, v151
	v_mul_f32_e32 v6, v6, v152
	v_mul_f32_e32 v7, v7, v153
	v_mul_f32_e32 v12, v12, v8
	v_mul_f32_e32 v13, v13, v9
	v_mul_f32_e32 v14, v14, v10
	v_mul_f32_e32 v15, v15, v11
	v_mul_f32_e32 v4, v4, v0
	v_mul_f32_e32 v5, v5, v1
	v_mul_f32_e32 v6, v6, v2
	v_mul_f32_e32 v7, v7, v3
	v_cvt_pk_bf16_f32 v8, v12, v13
	v_cvt_pk_bf16_f32 v9, v14, v15
	v_cvt_pk_bf16_f32 v10, v4, v5
	v_cvt_pk_bf16_f32 v11, v6, v7
	global_store_dwordx4 v[204:205], v[8:11], off
	s_waitcnt vmcnt(8)
	v_mbcnt_lo_u32_b32 v248, -1, 0
	v_mbcnt_hi_u32_b32 v248, -1, v248
	v_add_f32_e32 v208, v208, v209
	v_add_f32_e32 v210, v210, v211
	v_add_f32_e32 v212, v212, v213
	v_add_f32_e32 v214, v214, v215
	v_add_f32_e32 v216, v216, v217
	v_add_f32_e32 v218, v218, v219
	v_add_f32_e32 v220, v220, v221
	v_add_f32_e32 v222, v222, v223
	v_add_f32_e32 v224, v224, v225
	v_add_f32_e32 v226, v226, v227
	v_add_f32_e32 v228, v228, v229
	v_add_f32_e32 v230, v230, v231
	v_add_f32_e32 v232, v232, v233
	v_add_f32_e32 v234, v234, v235
	v_add_f32_e32 v236, v236, v237
	v_add_f32_e32 v238, v238, v239
	v_xor_b32_e32 v248, 16, v248
	v_lshlrev_b32_e32 v248, 2, v248
	v_add_f32_e32 v208, v208, v210
	v_add_f32_e32 v212, v212, v214
	v_add_f32_e32 v216, v216, v218
	v_add_f32_e32 v220, v220, v222
	v_add_f32_e32 v224, v224, v226
	v_add_f32_e32 v228, v228, v230
	v_add_f32_e32 v232, v232, v234
	v_add_f32_e32 v236, v236, v238
	ds_bpermute_b32 v209, v248, v208
	ds_bpermute_b32 v213, v248, v212
	ds_bpermute_b32 v217, v248, v216
	ds_bpermute_b32 v221, v248, v220
	ds_bpermute_b32 v225, v248, v224
	ds_bpermute_b32 v229, v248, v228
	ds_bpermute_b32 v233, v248, v232
	ds_bpermute_b32 v237, v248, v236
	s_waitcnt lgkmcnt(0)
	v_add_f32_e32 v208, v208, v209
	v_add_f32_e32 v212, v212, v213
	v_add_f32_e32 v216, v216, v217
	v_add_f32_e32 v220, v220, v221
	v_add_f32_e32 v224, v224, v225
	v_add_f32_e32 v228, v228, v229
	v_add_f32_e32 v232, v232, v233
	v_add_f32_e32 v236, v236, v237
	v_mov_b32_e32 v209, v208
	v_mov_b32_e32 v213, v212
	v_mov_b32_e32 v217, v216
	v_mov_b32_e32 v221, v220
	v_mov_b32_e32 v225, v224
	v_mov_b32_e32 v229, v228
	v_mov_b32_e32 v233, v232
	v_mov_b32_e32 v237, v236
	s_nop 1
	v_permlane32_swap_b32_e32 v208, v209
	v_permlane32_swap_b32_e32 v212, v213
	v_permlane32_swap_b32_e32 v216, v217
	v_permlane32_swap_b32_e32 v220, v221
	v_permlane32_swap_b32_e32 v224, v225
	v_permlane32_swap_b32_e32 v228, v229
	v_permlane32_swap_b32_e32 v232, v233
	v_permlane32_swap_b32_e32 v236, v237
	v_add_f32_e32 v208, v208, v209
	v_add_f32_e32 v212, v212, v213
	v_add_f32_e32 v216, v216, v217
	v_add_f32_e32 v220, v220, v221
	v_add_f32_e32 v224, v224, v225
	v_add_f32_e32 v228, v228, v229
	v_add_f32_e32 v232, v232, v233
	v_add_f32_e32 v236, v236, v237
	v_fmamk_f32 v208, v208, 0x3a800000, v177
	v_fmamk_f32 v212, v212, 0x3a800000, v177
	v_fmamk_f32 v216, v216, 0x3a800000, v177
	v_fmamk_f32 v220, v220, 0x3a800000, v177
	v_fmamk_f32 v224, v224, 0x3a800000, v177
	v_fmamk_f32 v228, v228, 0x3a800000, v177
	v_fmamk_f32 v232, v232, 0x3a800000, v177
	v_fmamk_f32 v236, v236, 0x3a800000, v177
	v_rsq_f32_e32 v240, v208
	v_rsq_f32_e32 v241, v212
	v_rsq_f32_e32 v242, v216
	v_rsq_f32_e32 v243, v220
	v_rsq_f32_e32 v244, v224
	v_rsq_f32_e32 v245, v228
	v_rsq_f32_e32 v246, v232
	v_rsq_f32_e32 v247, v236
	s_nop 0
	s_andn2_b64 vcc, exec, s[6:7]
	s_mov_b64 s[4:5], -1
	s_cbranch_vccnz .LBB0_479
	s_andn2_b64 vcc, exec, s[16:17]
	s_cbranch_vccnz .LBB0_478
	s_barrier
	s_branch .LBB0_478

.LBB0_1042:
	s_add_u32 s22, s6, 0x8800000
	s_addc_u32 s23, s7, 0
	s_lshl_b32 s24, s24, 5
	s_and_b32 s30, s24, 0x60
	s_mov_b64 s[24:25], 0x80
	s_add_i32 m0, s41, 0x18000
	v_lshl_add_u64 v[6:7], v[6:7], 0, s[24:25]
	s_lshl_b32 s9, s26, 13
	s_lshl_b32 s27, s30, 7
	s_waitcnt vmcnt(2)
	s_barrier
	global_load_lds_dwordx4 v[6:7], off
	v_lshl_add_u64 v[4:5], v[4:5], 0, s[24:25]
	s_add_i32 m0, s41, 0x1a000
	s_add_i32 s46, s41, 0x8000
	s_add_i32 s47, s41, 0xa000
	global_load_lds_dwordx4 v[4:5], off
	v_lshl_add_u64 v[0:1], v[0:1], 0, s[24:25]
	s_mov_b32 m0, s46
	s_add_u32 s28, s4, 0x40080
	global_load_lds_dwordx4 v[0:1], off
	v_lshl_add_u64 v[0:1], v[2:3], 0, s[24:25]
	s_mov_b32 m0, s47
	s_addc_u32 s29, s5, 0
	global_load_lds_dwordx4 v[0:1], off
	s_add_i32 m0, s41, 0x1c000
	v_lshl_add_u64 v[0:1], s[28:29], 0, v[132:133]
	global_load_lds_dwordx4 v[0:1], off
	v_lshl_add_u64 v[0:1], s[28:29], 0, v[128:129]
	s_add_i32 m0, s41, 0x1e000
	v_bfe_u32 v2, v8, 4, 2
	global_load_lds_dwordx4 v[0:1], off
	v_and_b32_e32 v1, 15, v8
	v_lshlrev_b32_e32 v0, 4, v2
	v_lshlrev_b32_e32 v3, 2, v8
	v_lshl_or_b32 v159, s26, 6, v1
	v_lshl_or_b32 v1, v1, 6, v0
	v_and_b32_e32 v3, 32, v3
	v_bitop3_b32 v4, v1, s9, v3 bitop3:0xde
	v_bitop3_b32 v165, v1, s27, v3 bitop3:0xde
	v_mov_b32_e32 v1, v133
	v_lshl_add_u64 v[0:1], s[6:7], 0, v[0:1]
	s_mov_b64 s[6:7], 0x200000
	v_lshl_add_u64 v[136:137], v[0:1], 0, s[6:7]
	v_lshlrev_b32_e32 v0, 14, v13
	v_and_b32_e32 v0, 0xffff8000, v0
	v_lshl_add_u32 v0, v12, 11, v0
	v_and_b32_e32 v1, 1, v13
	v_lshl_or_b32 v0, v1, 6, v0
	v_lshl_add_u32 v138, v14, 1, v0
	v_lshlrev_b32_e32 v0, 14, v9
	v_and_b32_e32 v0, 0xffff8000, v0
	s_waitcnt vmcnt(6)
	s_cmpk_lt_u32 s13, 0x100
	v_lshl_add_u32 v0, v10, 11, v0
	v_and_b32_e32 v1, 1, v9
	s_cselect_b64 s[26:27], -1, 0
	v_lshl_or_b32 v0, v1, 6, v0
	s_add_i32 s48, 0, 0x10000
	s_add_i32 s49, 0, 0x14000
	s_sext_i32_i16 s33, s12
	v_lshl_or_b32 v167, v2, 3, s30
	v_mov_b32_e32 v139, v133
	v_lshl_add_u32 v140, v11, 1, v0
	v_mov_b32_e32 v141, v133
	v_mov_b64_e32 v[142:143], 0xb00
	v_mov_b64_e32 v[144:145], 0xaff
	v_add_u32_e32 v169, s48, v165
	v_add_u32_e32 v171, s49, v165
	v_add_u32_e32 v173, 0, v4
	v_mov_b32_e32 v175, 0x3727c5ac
	s_mov_b32 s50, 0xf800000
	v_mov_b32_e32 v177, 0x260
	s_movk_i32 s51, 0x1600
	s_barrier
	v_lshl_add_u32 v249, s8, 8, v159
	s_mov_b64 s[60:61], 0x2000
	v_lshlrev_b32_e32 v204, 6, v249
	v_mov_b32_e32 v205, 0
	v_lshl_add_u64 v[204:205], v[136:137], 0, v[204:205]
	v_lshl_add_u64 v[206:207], v[204:205], 0, s[60:61]
	global_load_dwordx4 v[208:211], v[204:205], off
	global_load_dwordx4 v[212:215], v[204:205], off offset:1024
	global_load_dwordx4 v[216:219], v[204:205], off offset:2048
	global_load_dwordx4 v[220:223], v[204:205], off offset:3072
	global_load_dwordx4 v[224:227], v[206:207], off
	global_load_dwordx4 v[228:231], v[206:207], off offset:1024
	global_load_dwordx4 v[232:235], v[206:207], off offset:2048
	global_load_dwordx4 v[236:239], v[206:207], off offset:3072
	s_waitcnt vmcnt(0)
	v_mbcnt_lo_u32_b32 v248, -1, 0
	v_mbcnt_hi_u32_b32 v248, -1, v248
	v_add_f32_e32 v208, v208, v209
	v_add_f32_e32 v210, v210, v211
	v_add_f32_e32 v212, v212, v213
	v_add_f32_e32 v214, v214, v215
	v_add_f32_e32 v216, v216, v217
	v_add_f32_e32 v218, v218, v219
	v_add_f32_e32 v220, v220, v221
	v_add_f32_e32 v222, v222, v223
	v_add_f32_e32 v224, v224, v225
	v_add_f32_e32 v226, v226, v227
	v_add_f32_e32 v228, v228, v229
	v_add_f32_e32 v230, v230, v231
	v_add_f32_e32 v232, v232, v233
	v_add_f32_e32 v234, v234, v235
	v_add_f32_e32 v236, v236, v237
	v_add_f32_e32 v238, v238, v239
	v_xor_b32_e32 v248, 16, v248
	v_lshlrev_b32_e32 v248, 2, v248
	v_add_f32_e32 v208, v208, v210
	v_add_f32_e32 v212, v212, v214
	v_add_f32_e32 v216, v216, v218
	v_add_f32_e32 v220, v220, v222
	v_add_f32_e32 v224, v224, v226
	v_add_f32_e32 v228, v228, v230
	v_add_f32_e32 v232, v232, v234
	v_add_f32_e32 v236, v236, v238
	ds_bpermute_b32 v209, v248, v208
	ds_bpermute_b32 v213, v248, v212
	ds_bpermute_b32 v217, v248, v216
	ds_bpermute_b32 v221, v248, v220
	ds_bpermute_b32 v225, v248, v224
	ds_bpermute_b32 v229, v248, v228
	ds_bpermute_b32 v233, v248, v232
	ds_bpermute_b32 v237, v248, v236
	s_waitcnt lgkmcnt(0)
	v_add_f32_e32 v208, v208, v209
	v_add_f32_e32 v212, v212, v213
	v_add_f32_e32 v216, v216, v217
	v_add_f32_e32 v220, v220, v221
	v_add_f32_e32 v224, v224, v225
	v_add_f32_e32 v228, v228, v229
	v_add_f32_e32 v232, v232, v233
	v_add_f32_e32 v236, v236, v237
	v_mov_b32_e32 v209, v208
	v_mov_b32_e32 v213, v212
	v_mov_b32_e32 v217, v216
	v_mov_b32_e32 v221, v220
	v_mov_b32_e32 v225, v224
	v_mov_b32_e32 v229, v228
	v_mov_b32_e32 v233, v232
	v_mov_b32_e32 v237, v236
	s_nop 1
	v_permlane32_swap_b32_e32 v208, v209
	v_permlane32_swap_b32_e32 v212, v213
	v_permlane32_swap_b32_e32 v216, v217
	v_permlane32_swap_b32_e32 v220, v221
	v_permlane32_swap_b32_e32 v224, v225
	v_permlane32_swap_b32_e32 v228, v229
	v_permlane32_swap_b32_e32 v232, v233
	v_permlane32_swap_b32_e32 v236, v237
	v_add_f32_e32 v208, v208, v209
	v_add_f32_e32 v212, v212, v213
	v_add_f32_e32 v216, v216, v217
	v_add_f32_e32 v220, v220, v221
	v_add_f32_e32 v224, v224, v225
	v_add_f32_e32 v228, v228, v229
	v_add_f32_e32 v232, v232, v233
	v_add_f32_e32 v236, v236, v237
	v_fmamk_f32 v208, v208, 0x3a800000, v175
	v_fmamk_f32 v212, v212, 0x3a800000, v175
	v_fmamk_f32 v216, v216, 0x3a800000, v175
	v_fmamk_f32 v220, v220, 0x3a800000, v175
	v_fmamk_f32 v224, v224, 0x3a800000, v175
	v_fmamk_f32 v228, v228, 0x3a800000, v175
	v_fmamk_f32 v232, v232, 0x3a800000, v175
	v_fmamk_f32 v236, v236, 0x3a800000, v175
	v_rsq_f32_e32 v240, v208
	v_rsq_f32_e32 v241, v212
	v_rsq_f32_e32 v242, v216
	v_rsq_f32_e32 v243, v220
	v_rsq_f32_e32 v244, v224
	v_rsq_f32_e32 v245, v228
	v_rsq_f32_e32 v246, v232
	v_rsq_f32_e32 v247, v236
	s_nop 0
	s_branch .LBB0_1045

.LBB0_1051:
	s_cmp_lg_u64 s[6:7], 0
	s_cselect_b32 s62, s30, s8
	v_lshl_add_u32 v249, s62, 8, v159
	s_mov_b64 s[60:61], 0x2000
	v_lshlrev_b32_e32 v204, 6, v249
	v_mov_b32_e32 v205, 0
	v_lshl_add_u64 v[204:205], v[136:137], 0, v[204:205]
	v_lshl_add_u64 v[206:207], v[204:205], 0, s[60:61]
	global_load_dwordx4 v[208:211], v[204:205], off
	global_load_dwordx4 v[212:215], v[204:205], off offset:1024
	global_load_dwordx4 v[216:219], v[204:205], off offset:2048
	global_load_dwordx4 v[220:223], v[204:205], off offset:3072
	global_load_dwordx4 v[224:227], v[206:207], off
	global_load_dwordx4 v[228:231], v[206:207], off offset:1024
	global_load_dwordx4 v[232:235], v[206:207], off offset:2048
	global_load_dwordx4 v[236:239], v[206:207], off offset:3072
	v_lshl_or_b32 v252, s33, 7, v167
	v_lshlrev_b32_e32 v252, 1, v252
	v_mov_b32_e32 v253, 0
	v_lshl_add_u64 v[252:253], s[22:23], 0, v[252:253]
	v_lshl_add_u32 v206, s8, 8, v159
	v_mov_b32_e32 v154, v206
	v_mul_f32_e32 v207, 0xbfb8aa3b, v240
	v_mad_u64_u32 v[204:205], vcc, v154, s51, v[252:253]
	v_mul_f32_e32 v146, v124, v207
	v_mul_f32_e32 v147, v125, v207
	v_mul_f32_e32 v148, v126, v207
	v_mul_f32_e32 v149, v127, v207
	v_mul_f32_e32 v150, v116, v207
	v_mul_f32_e32 v151, v117, v207
	v_mul_f32_e32 v152, v118, v207
	v_mul_f32_e32 v153, v119, v207
	v_exp_f32_e32 v146, v146
	v_exp_f32_e32 v147, v147
	v_exp_f32_e32 v148, v148
	v_exp_f32_e32 v149, v149
	v_exp_f32_e32 v150, v150
	v_exp_f32_e32 v151, v151
	v_exp_f32_e32 v152, v152
	v_exp_f32_e32 v153, v153
	v_mul_f32_e32 v124, v124, v240
	v_mul_f32_e32 v125, v125, v240
	v_mul_f32_e32 v126, v126, v240
	v_mul_f32_e32 v127, v127, v240
	v_mul_f32_e32 v116, v116, v240
	v_mul_f32_e32 v117, v117, v240
	v_mul_f32_e32 v118, v118, v240
	v_mul_f32_e32 v119, v119, v240
	v_add_f32_e32 v146, 1.0, v146
	v_add_f32_e32 v147, 1.0, v147
	v_add_f32_e32 v148, 1.0, v148
	v_add_f32_e32 v149, 1.0, v149
	v_add_f32_e32 v150, 1.0, v150
	v_add_f32_e32 v151, 1.0, v151
	v_add_f32_e32 v152, 1.0, v152
	v_add_f32_e32 v153, 1.0, v153
	v_rcp_f32_e32 v146, v146
	v_rcp_f32_e32 v147, v147
	v_rcp_f32_e32 v148, v148
	v_rcp_f32_e32 v149, v149
	v_rcp_f32_e32 v150, v150
	v_rcp_f32_e32 v151, v151
	v_rcp_f32_e32 v152, v152
	v_rcp_f32_e32 v153, v153
	v_mul_f32_e32 v120, v120, v240
	v_mul_f32_e32 v121, v121, v240
	v_mul_f32_e32 v122, v122, v240
	v_mul_f32_e32 v123, v123, v240
	v_mul_f32_e32 v112, v112, v240
	v_mul_f32_e32 v113, v113, v240
	v_mul_f32_e32 v114, v114, v240
	v_mul_f32_e32 v115, v115, v240
	v_mul_f32_e32 v124, v124, v146
	v_mul_f32_e32 v125, v125, v147
	v_mul_f32_e32 v126, v126, v148
	v_mul_f32_e32 v127, v127, v149
	v_mul_f32_e32 v116, v116, v150
	v_mul_f32_e32 v117, v117, v151
	v_mul_f32_e32 v118, v118, v152
	v_mul_f32_e32 v119, v119, v153
	v_mul_f32_e32 v124, v124, v120
	v_mul_f32_e32 v125, v125, v121
	v_mul_f32_e32 v126, v126, v122
	v_mul_f32_e32 v127, v127, v123
	v_mul_f32_e32 v116, v116, v112
	v_mul_f32_e32 v117, v117, v113
	v_mul_f32_e32 v118, v118, v114
	v_mul_f32_e32 v119, v119, v115
	v_cvt_pk_bf16_f32 v120, v124, v125
	v_cvt_pk_bf16_f32 v121, v126, v127
	v_cvt_pk_bf16_f32 v122, v116, v117
	v_cvt_pk_bf16_f32 v123, v118, v119
	global_store_dwordx4 v[204:205], v[120:123], off
	v_add_u32_e32 v154, 16, v206
	v_mul_f32_e32 v207, 0xbfb8aa3b, v241
	v_mad_u64_u32 v[204:205], vcc, v154, s51, v[252:253]
	v_mul_f32_e32 v146, v108, v207
	v_mul_f32_e32 v147, v109, v207
	v_mul_f32_e32 v148, v110, v207
	v_mul_f32_e32 v149, v111, v207
	v_mul_f32_e32 v150, v100, v207
	v_mul_f32_e32 v151, v101, v207
	v_mul_f32_e32 v152, v102, v207
	v_mul_f32_e32 v153, v103, v207
	v_exp_f32_e32 v146, v146
	v_exp_f32_e32 v147, v147
	v_exp_f32_e32 v148, v148
	v_exp_f32_e32 v149, v149
	v_exp_f32_e32 v150, v150
	v_exp_f32_e32 v151, v151
	v_exp_f32_e32 v152, v152
	v_exp_f32_e32 v153, v153
	v_mul_f32_e32 v108, v108, v241
	v_mul_f32_e32 v109, v109, v241
	v_mul_f32_e32 v110, v110, v241
	v_mul_f32_e32 v111, v111, v241
	v_mul_f32_e32 v100, v100, v241
	v_mul_f32_e32 v101, v101, v241
	v_mul_f32_e32 v102, v102, v241
	v_mul_f32_e32 v103, v103, v241
	v_add_f32_e32 v146, 1.0, v146
	v_add_f32_e32 v147, 1.0, v147
	v_add_f32_e32 v148, 1.0, v148
	v_add_f32_e32 v149, 1.0, v149
	v_add_f32_e32 v150, 1.0, v150
	v_add_f32_e32 v151, 1.0, v151
	v_add_f32_e32 v152, 1.0, v152
	v_add_f32_e32 v153, 1.0, v153
	v_rcp_f32_e32 v146, v146
	v_rcp_f32_e32 v147, v147
	v_rcp_f32_e32 v148, v148
	v_rcp_f32_e32 v149, v149
	v_rcp_f32_e32 v150, v150
	v_rcp_f32_e32 v151, v151
	v_rcp_f32_e32 v152, v152
	v_rcp_f32_e32 v153, v153
	v_mul_f32_e32 v104, v104, v241
	v_mul_f32_e32 v105, v105, v241
	v_mul_f32_e32 v106, v106, v241
	v_mul_f32_e32 v107, v107, v241
	v_mul_f32_e32 v96, v96, v241
	v_mul_f32_e32 v97, v97, v241
	v_mul_f32_e32 v98, v98, v241
	v_mul_f32_e32 v99, v99, v241
	v_mul_f32_e32 v108, v108, v146
	v_mul_f32_e32 v109, v109, v147
	v_mul_f32_e32 v110, v110, v148
	v_mul_f32_e32 v111, v111, v149
	v_mul_f32_e32 v100, v100, v150
	v_mul_f32_e32 v101, v101, v151
	v_mul_f32_e32 v102, v102, v152
	v_mul_f32_e32 v103, v103, v153
	v_mul_f32_e32 v108, v108, v104
	v_mul_f32_e32 v109, v109, v105
	v_mul_f32_e32 v110, v110, v106
	v_mul_f32_e32 v111, v111, v107
	v_mul_f32_e32 v100, v100, v96
	v_mul_f32_e32 v101, v101, v97
	v_mul_f32_e32 v102, v102, v98
	v_mul_f32_e32 v103, v103, v99
	v_cvt_pk_bf16_f32 v104, v108, v109
	v_cvt_pk_bf16_f32 v105, v110, v111
	v_cvt_pk_bf16_f32 v106, v100, v101
	v_cvt_pk_bf16_f32 v107, v102, v103
	global_store_dwordx4 v[204:205], v[104:107], off
	v_add_u32_e32 v154, 32, v206
	v_mul_f32_e32 v207, 0xbfb8aa3b, v242
	v_mad_u64_u32 v[204:205], vcc, v154, s51, v[252:253]
	v_mul_f32_e32 v146, v92, v207
	v_mul_f32_e32 v147, v93, v207
	v_mul_f32_e32 v148, v94, v207
	v_mul_f32_e32 v149, v95, v207
	v_mul_f32_e32 v150, v84, v207
	v_mul_f32_e32 v151, v85, v207
	v_mul_f32_e32 v152, v86, v207
	v_mul_f32_e32 v153, v87, v207
	v_exp_f32_e32 v146, v146
	v_exp_f32_e32 v147, v147
	v_exp_f32_e32 v148, v148
	v_exp_f32_e32 v149, v149
	v_exp_f32_e32 v150, v150
	v_exp_f32_e32 v151, v151
	v_exp_f32_e32 v152, v152
	v_exp_f32_e32 v153, v153
	v_mul_f32_e32 v92, v92, v242
	v_mul_f32_e32 v93, v93, v242
	v_mul_f32_e32 v94, v94, v242
	v_mul_f32_e32 v95, v95, v242
	v_mul_f32_e32 v84, v84, v242
	v_mul_f32_e32 v85, v85, v242
	v_mul_f32_e32 v86, v86, v242
	v_mul_f32_e32 v87, v87, v242
	v_add_f32_e32 v146, 1.0, v146
	v_add_f32_e32 v147, 1.0, v147
	v_add_f32_e32 v148, 1.0, v148
	v_add_f32_e32 v149, 1.0, v149
	v_add_f32_e32 v150, 1.0, v150
	v_add_f32_e32 v151, 1.0, v151
	v_add_f32_e32 v152, 1.0, v152
	v_add_f32_e32 v153, 1.0, v153
	v_rcp_f32_e32 v146, v146
	v_rcp_f32_e32 v147, v147
	v_rcp_f32_e32 v148, v148
	v_rcp_f32_e32 v149, v149
	v_rcp_f32_e32 v150, v150
	v_rcp_f32_e32 v151, v151
	v_rcp_f32_e32 v152, v152
	v_rcp_f32_e32 v153, v153
	v_mul_f32_e32 v88, v88, v242
	v_mul_f32_e32 v89, v89, v242
	v_mul_f32_e32 v90, v90, v242
	v_mul_f32_e32 v91, v91, v242
	v_mul_f32_e32 v80, v80, v242
	v_mul_f32_e32 v81, v81, v242
	v_mul_f32_e32 v82, v82, v242
	v_mul_f32_e32 v83, v83, v242
	v_mul_f32_e32 v92, v92, v146
	v_mul_f32_e32 v93, v93, v147
	v_mul_f32_e32 v94, v94, v148
	v_mul_f32_e32 v95, v95, v149
	v_mul_f32_e32 v84, v84, v150
	v_mul_f32_e32 v85, v85, v151
	v_mul_f32_e32 v86, v86, v152
	v_mul_f32_e32 v87, v87, v153
	v_mul_f32_e32 v92, v92, v88
	v_mul_f32_e32 v93, v93, v89
	v_mul_f32_e32 v94, v94, v90
	v_mul_f32_e32 v95, v95, v91
	v_mul_f32_e32 v84, v84, v80
	v_mul_f32_e32 v85, v85, v81
	v_mul_f32_e32 v86, v86, v82
	v_mul_f32_e32 v87, v87, v83
	v_cvt_pk_bf16_f32 v88, v92, v93
	v_cvt_pk_bf16_f32 v89, v94, v95
	v_cvt_pk_bf16_f32 v90, v84, v85
	v_cvt_pk_bf16_f32 v91, v86, v87
	global_store_dwordx4 v[204:205], v[88:91], off
	v_add_u32_e32 v154, 48, v206
	v_mul_f32_e32 v207, 0xbfb8aa3b, v243
	v_mad_u64_u32 v[204:205], vcc, v154, s51, v[252:253]
	v_mul_f32_e32 v146, v76, v207
	v_mul_f32_e32 v147, v77, v207
	v_mul_f32_e32 v148, v78, v207
	v_mul_f32_e32 v149, v79, v207
	v_mul_f32_e32 v150, v68, v207
	v_mul_f32_e32 v151, v69, v207
	v_mul_f32_e32 v152, v70, v207
	v_mul_f32_e32 v153, v71, v207
	v_exp_f32_e32 v146, v146
	v_exp_f32_e32 v147, v147
	v_exp_f32_e32 v148, v148
	v_exp_f32_e32 v149, v149
	v_exp_f32_e32 v150, v150
	v_exp_f32_e32 v151, v151
	v_exp_f32_e32 v152, v152
	v_exp_f32_e32 v153, v153
	v_mul_f32_e32 v76, v76, v243
	v_mul_f32_e32 v77, v77, v243
	v_mul_f32_e32 v78, v78, v243
	v_mul_f32_e32 v79, v79, v243
	v_mul_f32_e32 v68, v68, v243
	v_mul_f32_e32 v69, v69, v243
	v_mul_f32_e32 v70, v70, v243
	v_mul_f32_e32 v71, v71, v243
	v_add_f32_e32 v146, 1.0, v146
	v_add_f32_e32 v147, 1.0, v147
	v_add_f32_e32 v148, 1.0, v148
	v_add_f32_e32 v149, 1.0, v149
	v_add_f32_e32 v150, 1.0, v150
	v_add_f32_e32 v151, 1.0, v151
	v_add_f32_e32 v152, 1.0, v152
	v_add_f32_e32 v153, 1.0, v153
	v_rcp_f32_e32 v146, v146
	v_rcp_f32_e32 v147, v147
	v_rcp_f32_e32 v148, v148
	v_rcp_f32_e32 v149, v149
	v_rcp_f32_e32 v150, v150
	v_rcp_f32_e32 v151, v151
	v_rcp_f32_e32 v152, v152
	v_rcp_f32_e32 v153, v153
	v_mul_f32_e32 v72, v72, v243
	v_mul_f32_e32 v73, v73, v243
	v_mul_f32_e32 v74, v74, v243
	v_mul_f32_e32 v75, v75, v243
	v_mul_f32_e32 v64, v64, v243
	v_mul_f32_e32 v65, v65, v243
	v_mul_f32_e32 v66, v66, v243
	v_mul_f32_e32 v67, v67, v243
	v_mul_f32_e32 v76, v76, v146
	v_mul_f32_e32 v77, v77, v147
	v_mul_f32_e32 v78, v78, v148
	v_mul_f32_e32 v79, v79, v149
	v_mul_f32_e32 v68, v68, v150
	v_mul_f32_e32 v69, v69, v151
	v_mul_f32_e32 v70, v70, v152
	v_mul_f32_e32 v71, v71, v153
	v_mul_f32_e32 v76, v76, v72
	v_mul_f32_e32 v77, v77, v73
	v_mul_f32_e32 v78, v78, v74
	v_mul_f32_e32 v79, v79, v75
	v_mul_f32_e32 v68, v68, v64
	v_mul_f32_e32 v69, v69, v65
	v_mul_f32_e32 v70, v70, v66
	v_mul_f32_e32 v71, v71, v67
	v_cvt_pk_bf16_f32 v72, v76, v77
	v_cvt_pk_bf16_f32 v73, v78, v79
	v_cvt_pk_bf16_f32 v74, v68, v69
	v_cvt_pk_bf16_f32 v75, v70, v71
	global_store_dwordx4 v[204:205], v[72:75], off
	v_add_u32_e32 v154, 128, v206
	v_mul_f32_e32 v207, 0xbfb8aa3b, v244
	v_mad_u64_u32 v[204:205], vcc, v154, s51, v[252:253]
	v_mul_f32_e32 v146, v60, v207
	v_mul_f32_e32 v147, v61, v207
	v_mul_f32_e32 v148, v62, v207
	v_mul_f32_e32 v149, v63, v207
	v_mul_f32_e32 v150, v52, v207
	v_mul_f32_e32 v151, v53, v207
	v_mul_f32_e32 v152, v54, v207
	v_mul_f32_e32 v153, v55, v207
	v_exp_f32_e32 v146, v146
	v_exp_f32_e32 v147, v147
	v_exp_f32_e32 v148, v148
	v_exp_f32_e32 v149, v149
	v_exp_f32_e32 v150, v150
	v_exp_f32_e32 v151, v151
	v_exp_f32_e32 v152, v152
	v_exp_f32_e32 v153, v153
	v_mul_f32_e32 v60, v60, v244
	v_mul_f32_e32 v61, v61, v244
	v_mul_f32_e32 v62, v62, v244
	v_mul_f32_e32 v63, v63, v244
	v_mul_f32_e32 v52, v52, v244
	v_mul_f32_e32 v53, v53, v244
	v_mul_f32_e32 v54, v54, v244
	v_mul_f32_e32 v55, v55, v244
	v_add_f32_e32 v146, 1.0, v146
	v_add_f32_e32 v147, 1.0, v147
	v_add_f32_e32 v148, 1.0, v148
	v_add_f32_e32 v149, 1.0, v149
	v_add_f32_e32 v150, 1.0, v150
	v_add_f32_e32 v151, 1.0, v151
	v_add_f32_e32 v152, 1.0, v152
	v_add_f32_e32 v153, 1.0, v153
	v_rcp_f32_e32 v146, v146
	v_rcp_f32_e32 v147, v147
	v_rcp_f32_e32 v148, v148
	v_rcp_f32_e32 v149, v149
	v_rcp_f32_e32 v150, v150
	v_rcp_f32_e32 v151, v151
	v_rcp_f32_e32 v152, v152
	v_rcp_f32_e32 v153, v153
	v_mul_f32_e32 v56, v56, v244
	v_mul_f32_e32 v57, v57, v244
	v_mul_f32_e32 v58, v58, v244
	v_mul_f32_e32 v59, v59, v244
	v_mul_f32_e32 v48, v48, v244
	v_mul_f32_e32 v49, v49, v244
	v_mul_f32_e32 v50, v50, v244
	v_mul_f32_e32 v51, v51, v244
	v_mul_f32_e32 v60, v60, v146
	v_mul_f32_e32 v61, v61, v147
	v_mul_f32_e32 v62, v62, v148
	v_mul_f32_e32 v63, v63, v149
	v_mul_f32_e32 v52, v52, v150
	v_mul_f32_e32 v53, v53, v151
	v_mul_f32_e32 v54, v54, v152
	v_mul_f32_e32 v55, v55, v153
	v_mul_f32_e32 v60, v60, v56
	v_mul_f32_e32 v61, v61, v57
	v_mul_f32_e32 v62, v62, v58
	v_mul_f32_e32 v63, v63, v59
	v_mul_f32_e32 v52, v52, v48
	v_mul_f32_e32 v53, v53, v49
	v_mul_f32_e32 v54, v54, v50
	v_mul_f32_e32 v55, v55, v51
	v_cvt_pk_bf16_f32 v56, v60, v61
	v_cvt_pk_bf16_f32 v57, v62, v63
	v_cvt_pk_bf16_f32 v58, v52, v53
	v_cvt_pk_bf16_f32 v59, v54, v55
	global_store_dwordx4 v[204:205], v[56:59], off
	v_add_u32_e32 v154, 144, v206
	v_mul_f32_e32 v207, 0xbfb8aa3b, v245
	v_mad_u64_u32 v[204:205], vcc, v154, s51, v[252:253]
	v_mul_f32_e32 v146, v44, v207
	v_mul_f32_e32 v147, v45, v207
	v_mul_f32_e32 v148, v46, v207
	v_mul_f32_e32 v149, v47, v207
	v_mul_f32_e32 v150, v36, v207
	v_mul_f32_e32 v151, v37, v207
	v_mul_f32_e32 v152, v38, v207
	v_mul_f32_e32 v153, v39, v207
	v_exp_f32_e32 v146, v146
	v_exp_f32_e32 v147, v147
	v_exp_f32_e32 v148, v148
	v_exp_f32_e32 v149, v149
	v_exp_f32_e32 v150, v150
	v_exp_f32_e32 v151, v151
	v_exp_f32_e32 v152, v152
	v_exp_f32_e32 v153, v153
	v_mul_f32_e32 v44, v44, v245
	v_mul_f32_e32 v45, v45, v245
	v_mul_f32_e32 v46, v46, v245
	v_mul_f32_e32 v47, v47, v245
	v_mul_f32_e32 v36, v36, v245
	v_mul_f32_e32 v37, v37, v245
	v_mul_f32_e32 v38, v38, v245
	v_mul_f32_e32 v39, v39, v245
	v_add_f32_e32 v146, 1.0, v146
	v_add_f32_e32 v147, 1.0, v147
	v_add_f32_e32 v148, 1.0, v148
	v_add_f32_e32 v149, 1.0, v149
	v_add_f32_e32 v150, 1.0, v150
	v_add_f32_e32 v151, 1.0, v151
	v_add_f32_e32 v152, 1.0, v152
	v_add_f32_e32 v153, 1.0, v153
	v_rcp_f32_e32 v146, v146
	v_rcp_f32_e32 v147, v147
	v_rcp_f32_e32 v148, v148
	v_rcp_f32_e32 v149, v149
	v_rcp_f32_e32 v150, v150
	v_rcp_f32_e32 v151, v151
	v_rcp_f32_e32 v152, v152
	v_rcp_f32_e32 v153, v153
	v_mul_f32_e32 v40, v40, v245
	v_mul_f32_e32 v41, v41, v245
	v_mul_f32_e32 v42, v42, v245
	v_mul_f32_e32 v43, v43, v245
	v_mul_f32_e32 v32, v32, v245
	v_mul_f32_e32 v33, v33, v245
	v_mul_f32_e32 v34, v34, v245
	v_mul_f32_e32 v35, v35, v245
	v_mul_f32_e32 v44, v44, v146
	v_mul_f32_e32 v45, v45, v147
	v_mul_f32_e32 v46, v46, v148
	v_mul_f32_e32 v47, v47, v149
	v_mul_f32_e32 v36, v36, v150
	v_mul_f32_e32 v37, v37, v151
	v_mul_f32_e32 v38, v38, v152
	v_mul_f32_e32 v39, v39, v153
	v_mul_f32_e32 v44, v44, v40
	v_mul_f32_e32 v45, v45, v41
	v_mul_f32_e32 v46, v46, v42
	v_mul_f32_e32 v47, v47, v43
	v_mul_f32_e32 v36, v36, v32
	v_mul_f32_e32 v37, v37, v33
	v_mul_f32_e32 v38, v38, v34
	v_mul_f32_e32 v39, v39, v35
	v_cvt_pk_bf16_f32 v40, v44, v45
	v_cvt_pk_bf16_f32 v41, v46, v47
	v_cvt_pk_bf16_f32 v42, v36, v37
	v_cvt_pk_bf16_f32 v43, v38, v39
	global_store_dwordx4 v[204:205], v[40:43], off
	v_add_u32_e32 v154, 160, v206
	v_mul_f32_e32 v207, 0xbfb8aa3b, v246
	v_mad_u64_u32 v[204:205], vcc, v154, s51, v[252:253]
	v_mul_f32_e32 v146, v28, v207
	v_mul_f32_e32 v147, v29, v207
	v_mul_f32_e32 v148, v30, v207
	v_mul_f32_e32 v149, v31, v207
	v_mul_f32_e32 v150, v20, v207
	v_mul_f32_e32 v151, v21, v207
	v_mul_f32_e32 v152, v22, v207
	v_mul_f32_e32 v153, v23, v207
	v_exp_f32_e32 v146, v146
	v_exp_f32_e32 v147, v147
	v_exp_f32_e32 v148, v148
	v_exp_f32_e32 v149, v149
	v_exp_f32_e32 v150, v150
	v_exp_f32_e32 v151, v151
	v_exp_f32_e32 v152, v152
	v_exp_f32_e32 v153, v153
	v_mul_f32_e32 v28, v28, v246
	v_mul_f32_e32 v29, v29, v246
	v_mul_f32_e32 v30, v30, v246
	v_mul_f32_e32 v31, v31, v246
	v_mul_f32_e32 v20, v20, v246
	v_mul_f32_e32 v21, v21, v246
	v_mul_f32_e32 v22, v22, v246
	v_mul_f32_e32 v23, v23, v246
	v_add_f32_e32 v146, 1.0, v146
	v_add_f32_e32 v147, 1.0, v147
	v_add_f32_e32 v148, 1.0, v148
	v_add_f32_e32 v149, 1.0, v149
	v_add_f32_e32 v150, 1.0, v150
	v_add_f32_e32 v151, 1.0, v151
	v_add_f32_e32 v152, 1.0, v152
	v_add_f32_e32 v153, 1.0, v153
	v_rcp_f32_e32 v146, v146
	v_rcp_f32_e32 v147, v147
	v_rcp_f32_e32 v148, v148
	v_rcp_f32_e32 v149, v149
	v_rcp_f32_e32 v150, v150
	v_rcp_f32_e32 v151, v151
	v_rcp_f32_e32 v152, v152
	v_rcp_f32_e32 v153, v153
	v_mul_f32_e32 v24, v24, v246
	v_mul_f32_e32 v25, v25, v246
	v_mul_f32_e32 v26, v26, v246
	v_mul_f32_e32 v27, v27, v246
	v_mul_f32_e32 v16, v16, v246
	v_mul_f32_e32 v17, v17, v246
	v_mul_f32_e32 v18, v18, v246
	v_mul_f32_e32 v19, v19, v246
	v_mul_f32_e32 v28, v28, v146
	v_mul_f32_e32 v29, v29, v147
	v_mul_f32_e32 v30, v30, v148
	v_mul_f32_e32 v31, v31, v149
	v_mul_f32_e32 v20, v20, v150
	v_mul_f32_e32 v21, v21, v151
	v_mul_f32_e32 v22, v22, v152
	v_mul_f32_e32 v23, v23, v153
	v_mul_f32_e32 v28, v28, v24
	v_mul_f32_e32 v29, v29, v25
	v_mul_f32_e32 v30, v30, v26
	v_mul_f32_e32 v31, v31, v27
	v_mul_f32_e32 v20, v20, v16
	v_mul_f32_e32 v21, v21, v17
	v_mul_f32_e32 v22, v22, v18
	v_mul_f32_e32 v23, v23, v19
	v_cvt_pk_bf16_f32 v24, v28, v29
	v_cvt_pk_bf16_f32 v25, v30, v31
	v_cvt_pk_bf16_f32 v26, v20, v21
	v_cvt_pk_bf16_f32 v27, v22, v23
	global_store_dwordx4 v[204:205], v[24:27], off
	v_add_u32_e32 v154, 176, v206
	v_mul_f32_e32 v207, 0xbfb8aa3b, v247
	v_mad_u64_u32 v[204:205], vcc, v154, s51, v[252:253]
	v_mul_f32_e32 v146, v12, v207
	v_mul_f32_e32 v147, v13, v207
	v_mul_f32_e32 v148, v14, v207
	v_mul_f32_e32 v149, v15, v207
	v_mul_f32_e32 v150, v4, v207
	v_mul_f32_e32 v151, v5, v207
	v_mul_f32_e32 v152, v6, v207
	v_mul_f32_e32 v153, v7, v207
	v_exp_f32_e32 v146, v146
	v_exp_f32_e32 v147, v147
	v_exp_f32_e32 v148, v148
	v_exp_f32_e32 v149, v149
	v_exp_f32_e32 v150, v150
	v_exp_f32_e32 v151, v151
	v_exp_f32_e32 v152, v152
	v_exp_f32_e32 v153, v153
	v_mul_f32_e32 v12, v12, v247
	v_mul_f32_e32 v13, v13, v247
	v_mul_f32_e32 v14, v14, v247
	v_mul_f32_e32 v15, v15, v247
	v_mul_f32_e32 v4, v4, v247
	v_mul_f32_e32 v5, v5, v247
	v_mul_f32_e32 v6, v6, v247
	v_mul_f32_e32 v7, v7, v247
	v_add_f32_e32 v146, 1.0, v146
	v_add_f32_e32 v147, 1.0, v147
	v_add_f32_e32 v148, 1.0, v148
	v_add_f32_e32 v149, 1.0, v149
	v_add_f32_e32 v150, 1.0, v150
	v_add_f32_e32 v151, 1.0, v151
	v_add_f32_e32 v152, 1.0, v152
	v_add_f32_e32 v153, 1.0, v153
	v_rcp_f32_e32 v146, v146
	v_rcp_f32_e32 v147, v147
	v_rcp_f32_e32 v148, v148
	v_rcp_f32_e32 v149, v149
	v_rcp_f32_e32 v150, v150
	v_rcp_f32_e32 v151, v151
	v_rcp_f32_e32 v152, v152
	v_rcp_f32_e32 v153, v153
	v_mul_f32_e32 v8, v8, v247
	v_mul_f32_e32 v9, v9, v247
	v_mul_f32_e32 v10, v10, v247
	v_mul_f32_e32 v11, v11, v247
	v_mul_f32_e32 v0, v0, v247
	v_mul_f32_e32 v1, v1, v247
	v_mul_f32_e32 v2, v2, v247
	v_mul_f32_e32 v3, v3, v247
	v_mul_f32_e32 v12, v12, v146
	v_mul_f32_e32 v13, v13, v147
	v_mul_f32_e32 v14, v14, v148
	v_mul_f32_e32 v15, v15, v149
	v_mul_f32_e32 v4, v4, v150
	v_mul_f32_e32 v5, v5, v151
	v_mul_f32_e32 v6, v6, v152
	v_mul_f32_e32 v7, v7, v153
	v_mul_f32_e32 v12, v12, v8
	v_mul_f32_e32 v13, v13, v9
	v_mul_f32_e32 v14, v14, v10
	v_mul_f32_e32 v15, v15, v11
	v_mul_f32_e32 v4, v4, v0
	v_mul_f32_e32 v5, v5, v1
	v_mul_f32_e32 v6, v6, v2
	v_mul_f32_e32 v7, v7, v3
	v_cvt_pk_bf16_f32 v8, v12, v13
	v_cvt_pk_bf16_f32 v9, v14, v15
	v_cvt_pk_bf16_f32 v10, v4, v5
	v_cvt_pk_bf16_f32 v11, v6, v7
	global_store_dwordx4 v[204:205], v[8:11], off
	s_waitcnt vmcnt(8)
	v_mbcnt_lo_u32_b32 v248, -1, 0
	v_mbcnt_hi_u32_b32 v248, -1, v248
	v_add_f32_e32 v208, v208, v209
	v_add_f32_e32 v210, v210, v211
	v_add_f32_e32 v212, v212, v213
	v_add_f32_e32 v214, v214, v215
	v_add_f32_e32 v216, v216, v217
	v_add_f32_e32 v218, v218, v219
	v_add_f32_e32 v220, v220, v221
	v_add_f32_e32 v222, v222, v223
	v_add_f32_e32 v224, v224, v225
	v_add_f32_e32 v226, v226, v227
	v_add_f32_e32 v228, v228, v229
	v_add_f32_e32 v230, v230, v231
	v_add_f32_e32 v232, v232, v233
	v_add_f32_e32 v234, v234, v235
	v_add_f32_e32 v236, v236, v237
	v_add_f32_e32 v238, v238, v239
	v_xor_b32_e32 v248, 16, v248
	v_lshlrev_b32_e32 v248, 2, v248
	v_add_f32_e32 v208, v208, v210
	v_add_f32_e32 v212, v212, v214
	v_add_f32_e32 v216, v216, v218
	v_add_f32_e32 v220, v220, v222
	v_add_f32_e32 v224, v224, v226
	v_add_f32_e32 v228, v228, v230
	v_add_f32_e32 v232, v232, v234
	v_add_f32_e32 v236, v236, v238
	ds_bpermute_b32 v209, v248, v208
	ds_bpermute_b32 v213, v248, v212
	ds_bpermute_b32 v217, v248, v216
	ds_bpermute_b32 v221, v248, v220
	ds_bpermute_b32 v225, v248, v224
	ds_bpermute_b32 v229, v248, v228
	ds_bpermute_b32 v233, v248, v232
	ds_bpermute_b32 v237, v248, v236
	s_waitcnt lgkmcnt(0)
	v_add_f32_e32 v208, v208, v209
	v_add_f32_e32 v212, v212, v213
	v_add_f32_e32 v216, v216, v217
	v_add_f32_e32 v220, v220, v221
	v_add_f32_e32 v224, v224, v225
	v_add_f32_e32 v228, v228, v229
	v_add_f32_e32 v232, v232, v233
	v_add_f32_e32 v236, v236, v237
	v_mov_b32_e32 v209, v208
	v_mov_b32_e32 v213, v212
	v_mov_b32_e32 v217, v216
	v_mov_b32_e32 v221, v220
	v_mov_b32_e32 v225, v224
	v_mov_b32_e32 v229, v228
	v_mov_b32_e32 v233, v232
	v_mov_b32_e32 v237, v236
	s_nop 1
	v_permlane32_swap_b32_e32 v208, v209
	v_permlane32_swap_b32_e32 v212, v213
	v_permlane32_swap_b32_e32 v216, v217
	v_permlane32_swap_b32_e32 v220, v221
	v_permlane32_swap_b32_e32 v224, v225
	v_permlane32_swap_b32_e32 v228, v229
	v_permlane32_swap_b32_e32 v232, v233
	v_permlane32_swap_b32_e32 v236, v237
	v_add_f32_e32 v208, v208, v209
	v_add_f32_e32 v212, v212, v213
	v_add_f32_e32 v216, v216, v217
	v_add_f32_e32 v220, v220, v221
	v_add_f32_e32 v224, v224, v225
	v_add_f32_e32 v228, v228, v229
	v_add_f32_e32 v232, v232, v233
	v_add_f32_e32 v236, v236, v237
	v_fmamk_f32 v208, v208, 0x3a800000, v175
	v_fmamk_f32 v212, v212, 0x3a800000, v175
	v_fmamk_f32 v216, v216, 0x3a800000, v175
	v_fmamk_f32 v220, v220, 0x3a800000, v175
	v_fmamk_f32 v224, v224, 0x3a800000, v175
	v_fmamk_f32 v228, v228, 0x3a800000, v175
	v_fmamk_f32 v232, v232, 0x3a800000, v175
	v_fmamk_f32 v236, v236, 0x3a800000, v175
	v_rsq_f32_e32 v240, v208
	v_rsq_f32_e32 v241, v212
	v_rsq_f32_e32 v242, v216
	v_rsq_f32_e32 v243, v220
	v_rsq_f32_e32 v244, v224
	v_rsq_f32_e32 v245, v228
	v_rsq_f32_e32 v246, v232
	v_rsq_f32_e32 v247, v236
	s_nop 0
	s_andn2_b64 vcc, exec, s[6:7]
	s_mov_b64 s[4:5], -1
	s_cbranch_vccnz .LBB0_1044
	s_andn2_b64 vcc, exec, s[16:17]
	s_cbranch_vccnz .LBB0_1043
	s_barrier
	s_branch .LBB0_1043
